# p8 per-unit prepare waits only for its hoisted loads (vmcnt(10)), not for the epilogue's store acks
# baseline (speedup 1.0000x reference)
; __device__ __forceinline__ float bf_lo(unsigned w) { return __uint_as_float(w << 16); }
; __device__ __forceinline__ float bf_hi(unsigned w) { return __uint_as_float(w & 0xffff0000u); }
; __device__ __forceinline__ u32x4 pack8(const f32x4 a, const f32x4 b) { u32x4 w; w.x = cvt_pk_bf16(a[0], a[1]); w.y = cvt_pk_bf16(a[2], a[3]); w.z = cvt_pk_bf16(b[0], b[1]); w.w = cvt_pk_bf16(b[2], b[3]); return w; }
;     __device__ __forceinline__ void operator()(const f32x4 (&acc)[2][2][4][2], const pg8::Unit& u, int wr, int wc, int fr, int fq, LAS unsigned char* lds, int par) const {
;     ...
;                 const int row = row0 + ai * 128 + m * 16, lrow = ai * 128 + wr * 64 + m * 16 + fr;
;                 float mu = 0.f, rstd = 1.f; if (fold) { mu = rsb[2 * lrow]; rstd = rsb[2 * lrow + 1]; }
; #pragma unroll
;                 for (int bj = 0; bj < 2; ++bj) {
;                     const size_t off = (size_t)row * ld + c0 + bj * 8;
;                     f32x4 v0 = acc[ai][bj][m][0], v1 = acc[ai][bj][m][1];
;                     if (fold) fold_apply(v0, v1, mu, rstd, cvb, wc * 64 + 16 * fq + bj * 8);
;                     if (MODE == 0) { v0 *= scale; v1 *= scale; }
;                     if (MODE == 1) {
; #pragma unroll
;                         for (int j = 0; j < 4; ++j) { const float a = fmaxf(v0[j], 0.f), b = fmaxf(v1[j], 0.f); v0[j] = a * a; v1[j] = b * b; }
;                     }
;                     if (MODE == 2 || MODE == 3) {
;                         const u32x4 gw = *(const u32x4*)(gate + off);
;                         v0[0] *= bf_lo(gw.x); v0[1] *= bf_hi(gw.x); v0[2] *= bf_lo(gw.y); v0[3] *= bf_hi(gw.y);
;                         v1[0] *= bf_lo(gw.z); v1[1] *= bf_hi(gw.z); v1[2] *= bf_lo(gw.w); v1[3] *= bf_hi(gw.w);
;                     }
;                     if (MODE == 3) {
;                         const u32x4 pw = *(const u32x4*)(o + off);
;                         v0[0] += bf_lo(pw.x); v0[1] += bf_hi(pw.x); v0[2] += bf_lo(pw.y); v0[3] += bf_hi(pw.y);
;                         v1[0] += bf_lo(pw.z); v1[1] += bf_hi(pw.z); v1[2] += bf_lo(pw.w); v1[3] += bf_hi(pw.w);
;                     }
;                     *(u32x4*)(o + off) = pack8(v0, v1);
.Lprep3_skip:
	v_mul_f32_e32 v200, v179, v178
	v_add_u32_e32 v155, 0xc0000, v201
	v_fma_f32 v188, -v200, v212, v213
	v_fma_f32 v189, -v200, v214, v215
	v_fma_f32 v190, -v200, v216, v217
	v_fma_f32 v191, -v200, v218, v219
	v_fma_f32 v192, -v200, v220, v221
	v_fma_f32 v193, -v200, v222, v223
	v_fma_f32 v194, -v200, v224, v225
	v_fma_f32 v195, -v200, v226, v227
	v_fma_f32 v78, v179, v78, v188
	v_fma_f32 v79, v179, v79, v189
	v_fma_f32 v80, v179, v80, v190
	v_fma_f32 v81, v179, v81, v191
	v_fma_f32 v74, v179, v74, v192
	v_fma_f32 v75, v179, v75, v193
	v_fma_f32 v76, v179, v76, v194
	v_fma_f32 v77, v179, v77, v195
	v_max_f32_e32 v78, 0, v78
	v_max_f32_e32 v79, 0, v79
	v_max_f32_e32 v80, 0, v80
	v_max_f32_e32 v81, 0, v81
	v_max_f32_e32 v74, 0, v74
	v_max_f32_e32 v75, 0, v75
	v_max_f32_e32 v76, 0, v76
	v_max_f32_e32 v77, 0, v77
	v_mul_f32_e32 v78, v78, v78
	v_mul_f32_e32 v79, v79, v79
	v_mul_f32_e32 v80, v80, v80
	v_mul_f32_e32 v81, v81, v81
	v_mul_f32_e32 v74, v74, v74
	v_mul_f32_e32 v75, v75, v75
	v_mul_f32_e32 v76, v76, v76
	v_mul_f32_e32 v77, v77, v77
	v_cvt_pk_bf16_f32 v196, v78, v79
	v_cvt_pk_bf16_f32 v197, v80, v81
	v_cvt_pk_bf16_f32 v198, v74, v75
	v_cvt_pk_bf16_f32 v199, v76, v77
	global_store_dwordx4 v155, v[196:199], s[26:27]
	v_fma_f32 v188, -v200, v228, v229
	v_fma_f32 v189, -v200, v230, v231
	v_fma_f32 v190, -v200, v232, v233
	v_fma_f32 v191, -v200, v234, v235
	v_fma_f32 v192, -v200, v236, v237
	v_fma_f32 v193, -v200, v238, v239
	v_fma_f32 v194, -v200, v240, v241
	v_fma_f32 v195, -v200, v242, v243
	v_fma_f32 v70, v179, v70, v188
	v_fma_f32 v71, v179, v71, v189
	v_fma_f32 v72, v179, v72, v190
	v_fma_f32 v73, v179, v73, v191
	v_fma_f32 v66, v179, v66, v192
	v_fma_f32 v67, v179, v67, v193
	v_fma_f32 v68, v179, v68, v194
	v_fma_f32 v69, v179, v69, v195
	v_max_f32_e32 v70, 0, v70
	v_max_f32_e32 v71, 0, v71
	v_max_f32_e32 v72, 0, v72
	v_max_f32_e32 v73, 0, v73
	v_max_f32_e32 v66, 0, v66
	v_max_f32_e32 v67, 0, v67
	v_max_f32_e32 v68, 0, v68
	v_max_f32_e32 v69, 0, v69
	v_mul_f32_e32 v70, v70, v70
	v_mul_f32_e32 v71, v71, v71
	v_mul_f32_e32 v72, v72, v72
	v_mul_f32_e32 v73, v73, v73
	v_mul_f32_e32 v66, v66, v66
	v_mul_f32_e32 v67, v67, v67
	v_mul_f32_e32 v68, v68, v68
	v_mul_f32_e32 v69, v69, v69
	v_cvt_pk_bf16_f32 v196, v70, v71
	v_cvt_pk_bf16_f32 v197, v72, v73
	v_cvt_pk_bf16_f32 v198, v66, v67
	v_cvt_pk_bf16_f32 v199, v68, v69
	global_store_dwordx4 v155, v[196:199], s[26:27] offset:16
	v_mul_f32_e32 v200, v181, v180
	v_add_u32_e32 v155, 0x200000, v201
	v_fma_f32 v188, -v200, v212, v213
	v_fma_f32 v189, -v200, v214, v215
	v_fma_f32 v190, -v200, v216, v217
	v_fma_f32 v191, -v200, v218, v219
	v_fma_f32 v192, -v200, v220, v221
	v_fma_f32 v193, -v200, v222, v223
	v_fma_f32 v194, -v200, v224, v225
	v_fma_f32 v195, -v200, v226, v227
	v_fma_f32 v62, v181, v62, v188
	v_fma_f32 v63, v181, v63, v189
	v_fma_f32 v64, v181, v64, v190
	v_fma_f32 v65, v181, v65, v191
	v_fma_f32 v58, v181, v58, v192
	v_fma_f32 v59, v181, v59, v193
	v_fma_f32 v60, v181, v60, v194
	v_fma_f32 v61, v181, v61, v195
	v_max_f32_e32 v62, 0, v62
	v_max_f32_e32 v63, 0, v63
	v_max_f32_e32 v64, 0, v64
	v_max_f32_e32 v65, 0, v65
	v_max_f32_e32 v58, 0, v58
	v_max_f32_e32 v59, 0, v59
	v_max_f32_e32 v60, 0, v60
	v_max_f32_e32 v61, 0, v61
	v_mul_f32_e32 v62, v62, v62
	v_mul_f32_e32 v63, v63, v63
	v_mul_f32_e32 v64, v64, v64
	v_mul_f32_e32 v65, v65, v65
	v_mul_f32_e32 v58, v58, v58
	v_mul_f32_e32 v59, v59, v59
	v_mul_f32_e32 v60, v60, v60
	v_mul_f32_e32 v61, v61, v61
	v_cvt_pk_bf16_f32 v196, v62, v63
	v_cvt_pk_bf16_f32 v197, v64, v65
	v_cvt_pk_bf16_f32 v198, v58, v59
	v_cvt_pk_bf16_f32 v199, v60, v61
	global_store_dwordx4 v155, v[196:199], s[26:27]
	v_fma_f32 v188, -v200, v228, v229
	v_fma_f32 v189, -v200, v230, v231
	v_fma_f32 v190, -v200, v232, v233
	v_fma_f32 v191, -v200, v234, v235
	v_fma_f32 v192, -v200, v236, v237
	v_fma_f32 v193, -v200, v238, v239
	v_fma_f32 v194, -v200, v240, v241
	v_fma_f32 v195, -v200, v242, v243
	v_fma_f32 v54, v181, v54, v188
	v_fma_f32 v55, v181, v55, v189
	v_fma_f32 v56, v181, v56, v190
	v_fma_f32 v57, v181, v57, v191
	v_fma_f32 v50, v181, v50, v192
	v_fma_f32 v51, v181, v51, v193
	v_fma_f32 v52, v181, v52, v194
	v_fma_f32 v53, v181, v53, v195
	v_max_f32_e32 v54, 0, v54
	v_max_f32_e32 v55, 0, v55
	v_max_f32_e32 v56, 0, v56
	v_max_f32_e32 v57, 0, v57
	v_max_f32_e32 v50, 0, v50
	v_max_f32_e32 v51, 0, v51
	v_max_f32_e32 v52, 0, v52
	v_max_f32_e32 v53, 0, v53
	v_mul_f32_e32 v54, v54, v54
	v_mul_f32_e32 v55, v55, v55
	v_mul_f32_e32 v56, v56, v56
	v_mul_f32_e32 v57, v57, v57
	v_mul_f32_e32 v50, v50, v50
	v_mul_f32_e32 v51, v51, v51
	v_mul_f32_e32 v52, v52, v52
	v_mul_f32_e32 v53, v53, v53
	v_cvt_pk_bf16_f32 v196, v54, v55
	v_cvt_pk_bf16_f32 v197, v56, v57
	v_cvt_pk_bf16_f32 v198, v50, v51
	v_cvt_pk_bf16_f32 v199, v52, v53
	global_store_dwordx4 v155, v[196:199], s[26:27] offset:16
	v_mul_f32_e32 v200, v183, v182
	v_add_u32_e32 v155, 0x240000, v201
	v_fma_f32 v188, -v200, v212, v213
	v_fma_f32 v189, -v200, v214, v215
	v_fma_f32 v190, -v200, v216, v217
	v_fma_f32 v191, -v200, v218, v219
	v_fma_f32 v192, -v200, v220, v221
	v_fma_f32 v193, -v200, v222, v223
	v_fma_f32 v194, -v200, v224, v225
	v_fma_f32 v195, -v200, v226, v227
	v_fma_f32 v46, v183, v46, v188
	v_fma_f32 v47, v183, v47, v189
	v_fma_f32 v48, v183, v48, v190
	v_fma_f32 v49, v183, v49, v191
	v_fma_f32 v42, v183, v42, v192
	v_fma_f32 v43, v183, v43, v193
	v_fma_f32 v44, v183, v44, v194
	v_fma_f32 v45, v183, v45, v195
	v_max_f32_e32 v46, 0, v46
	v_max_f32_e32 v47, 0, v47
	v_max_f32_e32 v48, 0, v48
	v_max_f32_e32 v49, 0, v49
	v_max_f32_e32 v42, 0, v42
	v_max_f32_e32 v43, 0, v43
	v_max_f32_e32 v44, 0, v44
; __device__ __forceinline__ float bf_lo(unsigned w) { return __uint_as_float(w << 16); }
; __device__ __forceinline__ float bf_hi(unsigned w) { return __uint_as_float(w & 0xffff0000u); }
; __device__ __forceinline__ u32x4 pack8(const f32x4 a, const f32x4 b) { u32x4 w; w.x = cvt_pk_bf16(a[0], a[1]); w.y = cvt_pk_bf16(a[2], a[3]); w.z = cvt_pk_bf16(b[0], b[1]); w.w = cvt_pk_bf16(b[2], b[3]); return w; }
;     __device__ __forceinline__ void operator()(const f32x4 (&acc)[2][2][4][2], const pg8::Unit& u, int wr, int wc, int fr, int fq, LAS unsigned char* lds, int par) const {
;     ...
;                 const int row = row0 + ai * 128 + m * 16, lrow = ai * 128 + wr * 64 + m * 16 + fr;
;                 float mu = 0.f, rstd = 1.f; if (fold) { mu = rsb[2 * lrow]; rstd = rsb[2 * lrow + 1]; }
; #pragma unroll
;                 for (int bj = 0; bj < 2; ++bj) {
;                     const size_t off = (size_t)row * ld + c0 + bj * 8;
;                     f32x4 v0 = acc[ai][bj][m][0], v1 = acc[ai][bj][m][1];
;                     if (fold) fold_apply(v0, v1, mu, rstd, cvb, wc * 64 + 16 * fq + bj * 8);
;                     if (MODE == 0) { v0 *= scale; v1 *= scale; }
;                     if (MODE == 1) {
; #pragma unroll
;                         for (int j = 0; j < 4; ++j) { const float a = fmaxf(v0[j], 0.f), b = fmaxf(v1[j], 0.f); v0[j] = a * a; v1[j] = b * b; }
;                     }
;                     if (MODE == 2 || MODE == 3) {
;                         const u32x4 gw = *(const u32x4*)(gate + off);
;                         v0[0] *= bf_lo(gw.x); v0[1] *= bf_hi(gw.x); v0[2] *= bf_lo(gw.y); v0[3] *= bf_hi(gw.y);
;                         v1[0] *= bf_lo(gw.z); v1[1] *= bf_hi(gw.z); v1[2] *= bf_lo(gw.w); v1[3] *= bf_hi(gw.w);
;                     }
;                     if (MODE == 3) {
;                         const u32x4 pw = *(const u32x4*)(o + off);
;                         v0[0] += bf_lo(pw.x); v0[1] += bf_hi(pw.x); v0[2] += bf_lo(pw.y); v0[3] += bf_hi(pw.y);
;                         v1[0] += bf_lo(pw.z); v1[1] += bf_hi(pw.z); v1[2] += bf_lo(pw.w); v1[3] += bf_hi(pw.w);
;                     }
;                     *(u32x4*)(o + off) = pack8(v0, v1);
	v_max_f32_e32 v45, 0, v45
	v_mul_f32_e32 v46, v46, v46
	v_mul_f32_e32 v47, v47, v47
	v_mul_f32_e32 v48, v48, v48
	v_mul_f32_e32 v49, v49, v49
	v_mul_f32_e32 v42, v42, v42
	v_mul_f32_e32 v43, v43, v43
	v_mul_f32_e32 v44, v44, v44
	v_mul_f32_e32 v45, v45, v45
	v_cvt_pk_bf16_f32 v196, v46, v47
	v_cvt_pk_bf16_f32 v197, v48, v49
	v_cvt_pk_bf16_f32 v198, v42, v43
	v_cvt_pk_bf16_f32 v199, v44, v45
	global_store_dwordx4 v155, v[196:199], s[26:27]
	v_fma_f32 v188, -v200, v228, v229
	v_fma_f32 v189, -v200, v230, v231
	v_fma_f32 v190, -v200, v232, v233
	v_fma_f32 v191, -v200, v234, v235
	v_fma_f32 v192, -v200, v236, v237
	v_fma_f32 v193, -v200, v238, v239
	v_fma_f32 v194, -v200, v240, v241
	v_fma_f32 v195, -v200, v242, v243
	v_fma_f32 v38, v183, v38, v188
	v_fma_f32 v39, v183, v39, v189
	v_fma_f32 v40, v183, v40, v190
	v_fma_f32 v41, v183, v41, v191
	v_fma_f32 v34, v183, v34, v192
	v_fma_f32 v35, v183, v35, v193
	v_fma_f32 v36, v183, v36, v194
	v_fma_f32 v37, v183, v37, v195
	v_max_f32_e32 v38, 0, v38
	v_max_f32_e32 v39, 0, v39
	v_max_f32_e32 v40, 0, v40
	v_max_f32_e32 v41, 0, v41
	v_max_f32_e32 v34, 0, v34
	v_max_f32_e32 v35, 0, v35
	v_max_f32_e32 v36, 0, v36
	v_max_f32_e32 v37, 0, v37
	v_mul_f32_e32 v38, v38, v38
	v_mul_f32_e32 v39, v39, v39
	v_mul_f32_e32 v40, v40, v40
	v_mul_f32_e32 v41, v41, v41
	v_mul_f32_e32 v34, v34, v34
	v_mul_f32_e32 v35, v35, v35
	v_mul_f32_e32 v36, v36, v36
	v_mul_f32_e32 v37, v37, v37
	v_cvt_pk_bf16_f32 v196, v38, v39
	v_cvt_pk_bf16_f32 v197, v40, v41
	v_cvt_pk_bf16_f32 v198, v34, v35
	v_cvt_pk_bf16_f32 v199, v36, v37
	global_store_dwordx4 v155, v[196:199], s[26:27] offset:16
	v_mul_f32_e32 v200, v185, v184
	v_add_u32_e32 v155, 0x280000, v201
	v_fma_f32 v188, -v200, v212, v213
	v_fma_f32 v189, -v200, v214, v215
	v_fma_f32 v190, -v200, v216, v217
	v_fma_f32 v191, -v200, v218, v219
	v_fma_f32 v192, -v200, v220, v221
	v_fma_f32 v193, -v200, v222, v223
	v_fma_f32 v194, -v200, v224, v225
	v_fma_f32 v195, -v200, v226, v227
	v_fma_f32 v30, v185, v30, v188
	v_fma_f32 v31, v185, v31, v189
	v_fma_f32 v32, v185, v32, v190
	v_fma_f32 v33, v185, v33, v191
	v_fma_f32 v26, v185, v26, v192
	v_fma_f32 v27, v185, v27, v193
	v_fma_f32 v28, v185, v28, v194
	v_fma_f32 v29, v185, v29, v195
	v_max_f32_e32 v30, 0, v30
	v_max_f32_e32 v31, 0, v31
	v_max_f32_e32 v32, 0, v32
	v_max_f32_e32 v33, 0, v33
	v_max_f32_e32 v26, 0, v26
	v_max_f32_e32 v27, 0, v27
	v_max_f32_e32 v28, 0, v28
	v_max_f32_e32 v29, 0, v29
	v_mul_f32_e32 v30, v30, v30
	v_mul_f32_e32 v31, v31, v31
	v_mul_f32_e32 v32, v32, v32
	v_mul_f32_e32 v33, v33, v33
	v_mul_f32_e32 v26, v26, v26
	v_mul_f32_e32 v27, v27, v27
	v_mul_f32_e32 v28, v28, v28
	v_mul_f32_e32 v29, v29, v29
	v_cvt_pk_bf16_f32 v196, v30, v31
	v_cvt_pk_bf16_f32 v197, v32, v33
	v_cvt_pk_bf16_f32 v198, v26, v27
	v_cvt_pk_bf16_f32 v199, v28, v29
	global_store_dwordx4 v155, v[196:199], s[26:27]
	v_fma_f32 v188, -v200, v228, v229
	v_fma_f32 v189, -v200, v230, v231
	v_fma_f32 v190, -v200, v232, v233
	v_fma_f32 v191, -v200, v234, v235
	v_fma_f32 v192, -v200, v236, v237
	v_fma_f32 v193, -v200, v238, v239
	v_fma_f32 v194, -v200, v240, v241
	v_fma_f32 v195, -v200, v242, v243
	v_fma_f32 v22, v185, v22, v188
	v_fma_f32 v23, v185, v23, v189
	v_fma_f32 v24, v185, v24, v190
	v_fma_f32 v25, v185, v25, v191
	v_fma_f32 v18, v185, v18, v192
	v_fma_f32 v19, v185, v19, v193
	v_fma_f32 v20, v185, v20, v194
	v_fma_f32 v21, v185, v21, v195
	v_max_f32_e32 v22, 0, v22
	v_max_f32_e32 v23, 0, v23
	v_max_f32_e32 v24, 0, v24
	v_max_f32_e32 v25, 0, v25
	v_max_f32_e32 v18, 0, v18
	v_max_f32_e32 v19, 0, v19
	v_max_f32_e32 v20, 0, v20
	v_max_f32_e32 v21, 0, v21
	v_mul_f32_e32 v22, v22, v22
	v_mul_f32_e32 v23, v23, v23
	v_mul_f32_e32 v24, v24, v24
	v_mul_f32_e32 v25, v25, v25
	v_mul_f32_e32 v18, v18, v18
	v_mul_f32_e32 v19, v19, v19
	v_mul_f32_e32 v20, v20, v20
	v_mul_f32_e32 v21, v21, v21
	v_cvt_pk_bf16_f32 v196, v22, v23
	v_cvt_pk_bf16_f32 v197, v24, v25
	v_cvt_pk_bf16_f32 v198, v18, v19
	v_cvt_pk_bf16_f32 v199, v20, v21
	global_store_dwordx4 v155, v[196:199], s[26:27] offset:16
	v_mul_f32_e32 v200, v187, v186
	v_add_u32_e32 v155, 0x2c0000, v201
	v_fma_f32 v188, -v200, v212, v213
	v_fma_f32 v189, -v200, v214, v215
	v_fma_f32 v190, -v200, v216, v217
	v_fma_f32 v191, -v200, v218, v219
	v_fma_f32 v192, -v200, v220, v221
	v_fma_f32 v193, -v200, v222, v223
	v_fma_f32 v194, -v200, v224, v225
	v_fma_f32 v195, -v200, v226, v227
	v_fma_f32 v14, v187, v14, v188
	v_fma_f32 v15, v187, v15, v189
	v_fma_f32 v16, v187, v16, v190
	v_fma_f32 v17, v187, v17, v191
	v_fma_f32 v10, v187, v10, v192
	v_fma_f32 v11, v187, v11, v193
	v_fma_f32 v12, v187, v12, v194
	v_fma_f32 v13, v187, v13, v195
	v_max_f32_e32 v14, 0, v14
	v_max_f32_e32 v15, 0, v15
	v_max_f32_e32 v16, 0, v16
	v_max_f32_e32 v17, 0, v17
	v_max_f32_e32 v10, 0, v10
	v_max_f32_e32 v11, 0, v11
	v_max_f32_e32 v12, 0, v12
	v_max_f32_e32 v13, 0, v13
	v_mul_f32_e32 v14, v14, v14
	v_mul_f32_e32 v15, v15, v15
	v_mul_f32_e32 v16, v16, v16
	v_mul_f32_e32 v17, v17, v17
	v_mul_f32_e32 v10, v10, v10
	v_mul_f32_e32 v11, v11, v11
	v_mul_f32_e32 v12, v12, v12
	v_mul_f32_e32 v13, v13, v13
	v_cvt_pk_bf16_f32 v196, v14, v15
	v_cvt_pk_bf16_f32 v197, v16, v17
	v_cvt_pk_bf16_f32 v198, v10, v11
	v_cvt_pk_bf16_f32 v199, v12, v13
	global_store_dwordx4 v155, v[196:199], s[26:27]
	v_fma_f32 v188, -v200, v228, v229
	v_fma_f32 v189, -v200, v230, v231
	v_fma_f32 v190, -v200, v232, v233
	v_fma_f32 v191, -v200, v234, v235
	v_fma_f32 v192, -v200, v236, v237
	v_fma_f32 v193, -v200, v238, v239
	v_fma_f32 v194, -v200, v240, v241
	v_fma_f32 v195, -v200, v242, v243
	v_fma_f32 v6, v187, v6, v188
	v_fma_f32 v7, v187, v7, v189
	v_fma_f32 v8, v187, v8, v190
	v_fma_f32 v9, v187, v9, v191
	v_fma_f32 v2, v187, v2, v192
	v_fma_f32 v3, v187, v3, v193
	v_fma_f32 v4, v187, v4, v194
	v_fma_f32 v5, v187, v5, v195
	v_max_f32_e32 v6, 0, v6
	v_max_f32_e32 v7, 0, v7
	v_max_f32_e32 v8, 0, v8
	v_max_f32_e32 v9, 0, v9
	v_max_f32_e32 v2, 0, v2
	v_max_f32_e32 v3, 0, v3
	v_max_f32_e32 v4, 0, v4
	v_max_f32_e32 v5, 0, v5
	v_mul_f32_e32 v6, v6, v6
	v_mul_f32_e32 v7, v7, v7
	v_mul_f32_e32 v8, v8, v8
	v_mul_f32_e32 v9, v9, v9
	v_mul_f32_e32 v2, v2, v2
	v_mul_f32_e32 v3, v3, v3
	v_mul_f32_e32 v4, v4, v4
	v_mul_f32_e32 v5, v5, v5
	v_cvt_pk_bf16_f32 v196, v6, v7
	v_cvt_pk_bf16_f32 v197, v8, v9
	v_cvt_pk_bf16_f32 v198, v2, v3
	v_cvt_pk_bf16_f32 v199, v4, v5
	global_store_dwordx4 v155, v[196:199], s[26:27] offset:16
	s_andn2_b64 vcc, exec, s[22:23]
	s_mov_b64 s[22:23], -1
	s_cbranch_vccnz .LBB0_164
; #define LAS __attribute__((address_space(3)))
; __device__ __forceinline__ float shflx(float v, int k, int lane) { return __int_as_float(__builtin_amdgcn_ds_bpermute((lane ^ k) << 2, __float_as_int(v))); }
;     __device__ __forceinline__ void prepare(const pg8::Unit& u, LAS unsigned char* lds, int par, int tid) const { F.prepare(u, lds, par, tid); }
;     __device__ __forceinline__ void prepare(const pg8::Unit& u, LAS unsigned char* lds, int par, int tid) const { F.prepare(u, lds, par, tid); }
;     __device__ __forceinline__ void prepare(const pg8::Unit& u, LAS unsigned char* lds, int par, int tid) const { F.prepare(u, lds, par, tid); }
;     __device__ __forceinline__ void prepare(const pg8::Unit& u, LAS unsigned char* lds, int par, int tid) const {
;         if (stats == nullptr) return;
;         const int h = tid >> 8, tt = tid & 255, rl = tt >> 1, part = tt & 1, lrow = (rl >> 6) * 128 + h * 64 + (rl & 63);
;         const float* sp = stats + ((size_t)(u.pm * 256 + lrow) * 32 + part * 16) * 2;
;         float s1 = 0.f, s2 = 0.f;
; #pragma unroll
;         for (int i = 0; i < 8; ++i) { const f32x4 v = *(const f32x4*)(sp + 4 * i); s1 += v[0] + v[2]; s2 += v[1] + v[3]; }
;         s1 += shflx(s1, 1, tid & 63); s2 += shflx(s2, 1, tid & 63);
;         const float mu = s1 * (1.f / D), var = s2 * (1.f / D) - mu * mu, rstd = __builtin_amdgcn_rsqf(var + LN_EPS);
;         if (part == 0) { LAS float* rs = (LAS float*)(lds + RS_OFF) + (par * 256 + lrow) * 2; rs[0] = mu; rs[1] = rstd; }
	s_nop 0
	s_and_b32 s15, s39, 1
	s_waitcnt vmcnt(10) lgkmcnt(0)
	v_add_f32_e32 v2, v126, v128
	v_add_f32_e32 v8, 0, v2
	v_add_f32_e32 v2, v127, v129
	v_add_f32_e32 v9, 0, v2
	v_add_f32_e32 v2, v122, v124
	v_add_f32_e32 v8, v8, v2
	v_add_f32_e32 v2, v123, v125
	v_add_f32_e32 v9, v9, v2
	v_add_f32_e32 v2, v118, v120
	v_add_f32_e32 v8, v8, v2
	v_add_f32_e32 v2, v119, v121
	v_add_f32_e32 v9, v9, v2
	v_add_f32_e32 v2, v114, v116
	v_add_f32_e32 v8, v8, v2
	v_add_f32_e32 v2, v115, v117
	v_add_f32_e32 v9, v9, v2
	v_add_f32_e32 v2, v110, v112
	v_add_f32_e32 v8, v8, v2
	v_add_f32_e32 v2, v111, v113
	v_add_f32_e32 v9, v9, v2
	v_add_f32_e32 v2, v106, v108
	v_add_f32_e32 v8, v8, v2
	v_add_f32_e32 v2, v107, v109
	v_add_f32_e32 v9, v9, v2
	v_add_f32_e32 v2, v102, v104
	v_add_f32_e32 v8, v8, v2
	v_add_f32_e32 v2, v103, v105
	v_add_f32_e32 v9, v9, v2
	v_add_f32_e32 v2, v98, v100
	v_add_f32_e32 v3, v99, v101
	v_add_f32_e32 v2, v8, v2
	v_add_f32_e32 v3, v9, v3
	ds_bpermute_b32 v4, v145, v2
	ds_bpermute_b32 v5, v145, v3
	s_and_saveexec_b64 s[22:23], s[0:1]
	s_cbranch_execz .LBB0_179
	s_waitcnt lgkmcnt(1)
	v_add_f32_e32 v2, v2, v4
	v_mul_f32_e32 v2, 0x3a000000, v2
	s_waitcnt lgkmcnt(0)
	v_add_f32_e32 v3, v3, v5
	v_mul_f32_e32 v4, v2, v2
	v_fma_f32 v3, v3, s61, -v4
	v_add_f32_e32 v3, 0x3727c5ac, v3
	v_rsq_f32_e32 v3, v3
	v_lshl_add_u32 v4, s15, 11, v151
	ds_write_b64 v4, v[2:3]
